# v022 + same V LDS-DMA hoist (issue next pair's V before the step-top wait, vmcnt(4)) in the o<15 attention loop
# speedup vs baseline: 1.0017x; 1.0017x over previous
; __device__ __forceinline__ void attn_pair_bases(int pi, int r4, int j0, int rowbase, int h, unsigned& ua, unsigned& ub) {
;     int rk, jtA; bool same; pair_decode(pi, r4, j0, rk, jtA, same);
;     const int jtB = jtA + 16;
;     const bool vA = (jtA >= 0) && (jtA < 2048), vB = (jtB >= 0) && (jtB < 2048);
;     const int jA = vA ? jtA : jtB, jB = vB ? jtB : jtA;
;     ua = (unsigned)(((rowbase + 4 * jA + rk) * AW + h * 64) * 2); ub = (unsigned)(((rowbase + 4 * jB + rk) * AW + h * 64) * 2);
; }
; __device__ __forceinline__ void attn_load_k(int pi, int r4, int j0, int rowbase, int h, int klo, __amdgpu_buffer_rsrc_t Kr, bf16x8 (&Kn)[4]) {
;     unsigned ua, ub; attn_pair_bases(pi, r4, j0, rowbase, h, ua, ub);
;     Kn[0] = __builtin_bit_cast(bf16x8, __builtin_amdgcn_raw_buffer_load_b128(Kr, klo, ua, 0)); Kn[1] = __builtin_bit_cast(bf16x8, __builtin_amdgcn_raw_buffer_load_b128(Kr, klo + 64, ua, 0));
;     Kn[2] = __builtin_bit_cast(bf16x8, __builtin_amdgcn_raw_buffer_load_b128(Kr, klo, ub, 0)); Kn[3] = __builtin_bit_cast(bf16x8, __builtin_amdgcn_raw_buffer_load_b128(Kr, klo + 64, ub, 0));
; }
; __device__ __forceinline__ void attn_dma_v(int pi, int r4, int j0, int rowbase, int h, int vlo, __amdgpu_buffer_rsrc_t Vr, LAS unsigned char* vbuf) {
;     unsigned ua, ub; attn_pair_bases(pi, r4, j0, rowbase, h, ua, ub);
;     __builtin_amdgcn_raw_ptr_buffer_load_lds(Vr, (LAS unsigned*)(vbuf), 16, vlo, ua, 0, 0);
;     __builtin_amdgcn_raw_ptr_buffer_load_lds(Vr, (LAS unsigned*)(vbuf + 1024), 16, vlo + 64, ua, 0, 0);
; template <int MODE, int DRY, int QLO, int QHI>
; __device__ __forceinline__ int attn_step(int o, int& par, const AttnCtx& C, const AttnLane& L, f32x4 (&O)[4][4], float (&mrun)[4], float (&lrun)[4], const bf16x8 (&Qf)[4][2], bf16x8 (&Kn)[4]) {
;     ...
;     asm volatile("s_waitcnt vmcnt(0)" ::: "memory");
;     bf16x8 Vf[4];
;     { LAS const unsigned char* vb = C.vl + par * 4096 + (4 * fq + (fr >> 2)) * 64 + (fr & 3) * 8;
; #pragma unroll
;       for (int dt = 0; dt < 4; ++dt) { const s16x4 lo = vtr(vb + (dt >> 1) * 1024 + (dt & 1) * 32), hi = vtr(vb + 2048 + (dt >> 1) * 1024 + (dt & 1) * 32);
;           Vf[dt] = (bf16x8){lo[0], lo[1], lo[2], lo[3], hi[0], hi[1], hi[2], hi[3]}; }
;       asm volatile("" ::: "memory"); }
;     if (DRY != 2) if (on < 27) attn_dma_v(pn, C.r4, C.j0, C.rowbase, C.h, C.vlo, C.Vr, C.vl + (par ^ 1) * 4096);
.LBB0_681:
	s_lshl_b32 s58, s83, 12
	v_add_u32_e32 v114, s58, v187
	v_cndmask_b32_e64 v128, 0, 1, s[42:43]
	v_cmp_ne_u32_e64 s[0:1], 1, v128
	s_andn2_b64 vcc, exec, s[42:43]
	s_cbranch_vccnz .Lmy_nodma_o15
	s_cmp_lt_i32 s66, 18
	s_mov_b32 s42, s63
	s_mov_b32 s15, s80
	s_mov_b32 s14, s66
	s_cbranch_scc1 .LBB0_684
	s_sub_i32 s14, s66, 18
	s_mul_i32 s15, s14, 0xab
	s_bfe_u32 s15, s15, 0x70009
	s_add_i32 s42, s82, s15
	s_and_b32 s42, s42, 3
	s_mul_i32 s15, s15, -3
	s_add_i32 s14, s15, s14
	s_or_b32 s42, s42, s78
	s_mov_b32 s15, s81
.LBB0_684:
	s_lshl_b32 s14, s14, 5
	s_xor_b32 s43, s58, 0x1000
	s_add_i32 s14, s14, s15
	s_add_i32 s43, s59, s43
	s_add_i32 s15, s14, 16
	s_cmpk_lt_u32 s14, 0x800
	s_cselect_b32 s58, s14, s15
	s_cmpk_lt_u32 s15, 0x800
	s_cselect_b32 s14, s15, s14
	s_lshl_b32 s15, s58, 2
	s_add_i32 s15, s15, s42
	s_mulk_i32 s15, 0x600
	s_lshl_b32 s14, s14, 2
	s_add_i32 s15, s15, s62
	s_add_i32 s14, s14, s42
	s_lshl_b32 s15, s15, 1
	s_mulk_i32 s14, 0x600
	s_mov_b32 m0, s43
	s_add_i32 s14, s14, s62
	buffer_load_dwordx4 v182, s[8:11], s15 offen lds
	s_add_i32 m0, s43, 0x400
	s_lshl_b32 s14, s14, 1
	buffer_load_dwordx4 v186, s[8:11], s15 offen lds
	s_add_i32 m0, s43, 0x800
	s_nop 0
	buffer_load_dwordx4 v182, s[8:11], s14 offen lds
	s_add_i32 m0, s43, 0xc00
	s_nop 0
	buffer_load_dwordx4 v186, s[8:11], s14 offen lds
	s_waitcnt vmcnt(4)
	s_branch .Lmy_join_o15

; #define LAS __attribute__((address_space(3)))
; __device__ __forceinline__ s16x4 vtr(LAS const unsigned char* p) { return __builtin_bit_cast(s16x4, __builtin_amdgcn_ds_read_tr16_b64_v4i16((LAS v4i16_t*)p)); }
; template <int MODE, int DRY, int QLO, int QHI>
; __device__ __forceinline__ int attn_step(int o, int& par, const AttnCtx& C, const AttnLane& L, f32x4 (&O)[4][4], float (&mrun)[4], float (&lrun)[4], const bf16x8 (&Qf)[4][2], bf16x8 (&Kn)[4]) {
;     ...
;     { LAS const unsigned char* vb = C.vl + par * 4096 + (4 * fq + (fr >> 2)) * 64 + (fr & 3) * 8;
; #pragma unroll
;       for (int dt = 0; dt < 4; ++dt) { const s16x4 lo = vtr(vb + (dt >> 1) * 1024 + (dt & 1) * 32), hi = vtr(vb + 2048 + (dt >> 1) * 1024 + (dt & 1) * 32);
;           Vf[dt] = (bf16x8){lo[0], lo[1], lo[2], lo[3], hi[0], hi[1], hi[2], hi[3]}; }
;       asm volatile("" ::: "memory"); }
;     if (DRY != 2) if (on < 27) attn_dma_v(pn, C.r4, C.j0, C.rowbase, C.h, C.vlo, C.Vr, C.vl + (par ^ 1) * 4096);
;     par ^= 1;
;     if (DRY == 1) {
;         asm volatile("" :: "v"(Kn[0]), "v"(Kn[1]), "v"(Kn[2]), "v"(Kn[3]), "v"(Vf[0]), "v"(Vf[1]), "v"(Vf[2]), "v"(Vf[3]));
;         if (on < 27) attn_load_k(pn, C.r4, C.j0, C.rowbase, C.h, C.klo, C.Kr, Kn);
;         return on;
;     }
;     f32x4 sA[4], sB[4];
; #pragma unroll
;     for (int qt = QLO; qt < QHI; ++qt) {
;         sA[qt] = __builtin_amdgcn_mfma_f32_16x16x32_bf16(Kn[0], Qf[qt][0], (f32x4){0.f, 0.f, 0.f, 0.f}, 0, 0, 0); sA[qt] = __builtin_amdgcn_mfma_f32_16x16x32_bf16(Kn[1], Qf[qt][1], sA[qt], 0, 0, 0);
;         sB[qt] = __builtin_amdgcn_mfma_f32_16x16x32_bf16(Kn[2], Qf[qt][0], (f32x4){0.f, 0.f, 0.f, 0.f}, 0, 0, 0); sB[qt] = __builtin_amdgcn_mfma_f32_16x16x32_bf16(Kn[3], Qf[qt][1], sB[qt], 0, 0, 0);
;     }
;     if (DRY != 2) if (on < 27) attn_load_k(pn, C.r4, C.j0, C.rowbase, C.h, C.klo, C.Kr, Kn);
.Lmy_join_o15:
	ds_read_b64_tr_b16 v[124:125], v114
	ds_read_b64_tr_b16 v[120:121], v114 offset:32
	ds_read_b64_tr_b16 v[116:117], v114 offset:1024
	ds_read_b64_tr_b16 v[112:113], v114 offset:1056
	ds_read_b64_tr_b16 v[126:127], v114 offset:2048
	ds_read_b64_tr_b16 v[122:123], v114 offset:2080
	ds_read_b64_tr_b16 v[118:119], v114 offset:3072
	ds_read_b64_tr_b16 v[114:115], v114 offset:3104
.LBB0_685:
	v_mfma_f32_16x16x32_bf16 v[128:131], v[100:103], v[80:83], 0
	s_and_b64 vcc, exec, s[0:1]
	v_mfma_f32_16x16x32_bf16 v[136:139], v[108:111], v[84:87], v[128:131]
	v_mfma_f32_16x16x32_bf16 v[128:131], v[96:99], v[80:83], 0
	v_mfma_f32_16x16x32_bf16 v[140:143], v[104:107], v[84:87], v[128:131]
	v_mfma_f32_16x16x32_bf16 v[128:131], v[100:103], v[88:91], 0
	v_mfma_f32_16x16x32_bf16 v[132:135], v[96:99], v[88:91], 0
	v_mfma_f32_16x16x32_bf16 v[128:131], v[108:111], v[92:95], v[128:131]
	v_mfma_f32_16x16x32_bf16 v[132:135], v[104:107], v[92:95], v[132:135]
	s_cbranch_vccnz .LBB0_690
	s_cmp_lt_i32 s66, 18
	s_cbranch_scc1 .LBB0_688
	s_sub_i32 s0, s66, 18
	s_mul_i32 s1, s0, 0xab
	s_bfe_u32 s1, s1, 0x70009
	s_add_i32 s14, s82, s1
	s_and_b32 s14, s14, 3
	s_mul_i32 s1, s1, -3
	s_add_i32 s66, s1, s0
	s_or_b32 s0, s14, s78
	s_mov_b32 s1, s81
	s_branch .LBB0_689
